# stagger variant: half of the teams delayed ~3.5us at P5 start
# baseline (speedup 1.0000x reference)
;     __host__ __device__ void init(int M_, int G_, int c_) { so.init(M_, 1024, G_, c_); }
;     __host__ __device__ void init(int M_, int G_, int c_) { so.init(M_, 3072, G_, c_); }
;     __host__ __device__ void init(int M_, int start_, int stride_, int limit_) { so.init(M_, 3072, stride_, start_); start = start_; stride = stride_; limit = limit_; }
; __device__ __forceinline__ unsigned long long rt() { return __builtin_amdgcn_s_memrealtime(); }
; __global__ void __launch_bounds__(NWAVES * 64, 2) fwd(Args args) {
;     ...
;     if (IN(5)) {
;         const unsigned long long amp_t0_5 = (PROBE_AMP == 5) ? rt() : 0ull;
;         _Pragma("unroll 1") for (int rep_ = 0; rep_ < ((PROBE == 5) ? 2 : 1); ++rep_) {
;         pg8::Gemm g{OAB, WBAB_T, M, D, 512, D, D, 1}; pg8::MergeOrder S; S.init(M, G, (int)blockIdx.x);
;         pg8::EpiMerge E{GAB, MRG};
;         pg8::gemm_phase<pg8::EpiMerge, pg8::MergeOrder, true, true>(lds + RING_OFF, g, S, E);
.LBB0_946:
	s_bfe_u32 s98, s2, 0x10003
	s_cmp_eq_u32 s98, 0
	s_cbranch_scc1 .Lstag_done
